# hgrn_sample z/onorm loads moved from behind the 16 nt state stores to the item top
# baseline (speedup 1.0000x reference)
.LBB0_324:
	v_mov_b32_e32 v0, 0
	v_readlane_b32 s2, v254, 7
	v_mbcnt_lo_u32_b32 v0, -1, v0
	v_mbcnt_hi_u32_b32 v82, -1, v0
	v_add_u32_e32 v68, s2, v82
	s_ashr_i32 s2, s0, 4
	s_add_i32 s6, s2, 0x4000
	s_ashr_i32 s7, s6, 31
	s_add_u32 s2, s6, s14
	s_addc_u32 s3, s7, 0
	s_lshl_b64 s[2:3], s[2:3], 8
	s_add_u32 s8, s16, s2
	s_addc_u32 s9, s17, s3
	v_cmp_gt_i32_e64 s[2:3], s1, v68
	v_ashrrev_i32_e32 v69, 31, v68
	v_lshl_add_u32 v83, v68, 2, s91
	s_waitcnt vmcnt(63) expcnt(7) lgkmcnt(15)
	s_barrier
	v_readlane_b32 s22, v254, 15
	v_readlane_b32 s23, v254, 16
	s_load_dwordx2 s[12:13], s[22:23], 0x20
	v_ashrrev_i32_e32 v141, 5, v68
	v_lshlrev_b32_e32 v0, 4, v82
	v_and_b32_e32 v6, 0x1f0, v0
	v_lshlrev_b32_e32 v0, 7, v141
	v_ashrrev_i32_e32 v1, 31, v0
	v_add_u32_e32 v4, 0x400, v0
	v_lshlrev_b64 v[36:37], 2, v[0:1]
	v_ashrrev_i32_e32 v5, 31, v4
	v_or_b32_e32 v36, v36, v6
	v_lshlrev_b64 v[38:39], 2, v[4:5]
	s_waitcnt lgkmcnt(0)
	v_lshl_add_u64 v[2:3], s[12:13], 0, v[36:37]
	v_or_b32_e32 v38, v38, v6
	v_lshl_add_u64 v[2:3], v[2:3], 0, s[4:5]
	v_lshl_add_u64 v[4:5], s[12:13], 0, v[38:39]
	v_lshl_add_u64 v[4:5], v[4:5], 0, s[4:5]
	global_load_dwordx4 v[24:27], v[2:3], off nt
	global_load_dwordx4 v[20:23], v[4:5], off nt
	v_add_u32_e32 v2, 0x800, v0
	v_ashrrev_i32_e32 v3, 31, v2
	v_add_u32_e32 v4, 0xc00, v0
	v_lshlrev_b64 v[70:71], 2, v[2:3]
	v_ashrrev_i32_e32 v5, 31, v4
	v_or_b32_e32 v70, v70, v6
	v_lshlrev_b64 v[72:73], 2, v[4:5]
	v_lshl_add_u64 v[2:3], s[12:13], 0, v[70:71]
	v_or_b32_e32 v72, v72, v6
	v_lshl_add_u64 v[2:3], v[2:3], 0, s[4:5]
	v_lshl_add_u64 v[4:5], s[12:13], 0, v[72:73]
	v_lshl_add_u64 v[4:5], v[4:5], 0, s[4:5]
	global_load_dwordx4 v[32:35], v[2:3], off nt
	global_load_dwordx4 v[28:31], v[4:5], off nt
	v_add_u32_e32 v2, 0x1000, v0
	v_ashrrev_i32_e32 v3, 31, v2
	v_add_u32_e32 v4, 0x1400, v0
	v_lshlrev_b64 v[74:75], 2, v[2:3]
	v_ashrrev_i32_e32 v5, 31, v4
	v_or_b32_e32 v74, v74, v6
	v_lshlrev_b64 v[76:77], 2, v[4:5]
	v_lshl_add_u64 v[2:3], s[12:13], 0, v[74:75]
	v_or_b32_e32 v76, v76, v6
	v_lshl_add_u64 v[2:3], v[2:3], 0, s[4:5]
	v_lshl_add_u64 v[4:5], s[12:13], 0, v[76:77]
	v_lshl_add_u64 v[4:5], v[4:5], 0, s[4:5]
	global_load_dwordx4 v[44:47], v[2:3], off nt
	global_load_dwordx4 v[40:43], v[4:5], off nt
	v_add_u32_e32 v2, 0x1800, v0
	v_ashrrev_i32_e32 v3, 31, v2
	v_add_u32_e32 v4, 0x1c00, v0
	v_lshlrev_b64 v[78:79], 2, v[2:3]
	v_ashrrev_i32_e32 v5, 31, v4
	v_or_b32_e32 v78, v78, v6
	v_lshlrev_b64 v[84:85], 2, v[4:5]
	v_lshl_add_u64 v[2:3], s[12:13], 0, v[78:79]
	v_or_b32_e32 v84, v84, v6
	v_lshl_add_u64 v[2:3], v[2:3], 0, s[4:5]
	v_lshl_add_u64 v[4:5], s[12:13], 0, v[84:85]
	v_lshl_add_u64 v[4:5], v[4:5], 0, s[4:5]
	global_load_dwordx4 v[52:55], v[2:3], off nt
	global_load_dwordx4 v[48:51], v[4:5], off nt
	v_add_u32_e32 v2, 0x2000, v0
	v_ashrrev_i32_e32 v3, 31, v2
	v_add_u32_e32 v4, 0x2400, v0
	v_lshlrev_b64 v[86:87], 2, v[2:3]
	v_ashrrev_i32_e32 v5, 31, v4
	v_or_b32_e32 v86, v86, v6
	v_lshlrev_b64 v[88:89], 2, v[4:5]
	v_lshl_add_u64 v[2:3], s[12:13], 0, v[86:87]
	v_or_b32_e32 v88, v88, v6
	v_lshl_add_u64 v[2:3], v[2:3], 0, s[4:5]
	v_lshl_add_u64 v[4:5], s[12:13], 0, v[88:89]
	v_lshl_add_u64 v[4:5], v[4:5], 0, s[4:5]
	global_load_dwordx4 v[60:63], v[2:3], off nt
	global_load_dwordx4 v[56:59], v[4:5], off nt
	v_add_u32_e32 v2, 0x2800, v0
	v_ashrrev_i32_e32 v3, 31, v2
	v_add_u32_e32 v4, 0x2c00, v0
	v_lshlrev_b64 v[90:91], 2, v[2:3]
	v_ashrrev_i32_e32 v5, 31, v4
	v_or_b32_e32 v90, v90, v6
	v_lshlrev_b64 v[92:93], 2, v[4:5]
	v_lshl_add_u64 v[2:3], s[12:13], 0, v[90:91]
	v_or_b32_e32 v92, v92, v6
	v_lshl_add_u64 v[2:3], v[2:3], 0, s[4:5]
	v_lshl_add_u64 v[4:5], s[12:13], 0, v[92:93]
	v_lshl_add_u64 v[4:5], v[4:5], 0, s[4:5]
	global_load_dwordx4 v[64:67], v[2:3], off nt
	global_load_dwordx4 v[16:19], v[4:5], off nt
	v_add_u32_e32 v2, 0x3000, v0
	v_ashrrev_i32_e32 v3, 31, v2
	v_add_u32_e32 v4, 0x3400, v0
	v_lshlrev_b64 v[94:95], 2, v[2:3]
	v_ashrrev_i32_e32 v5, 31, v4
	v_or_b32_e32 v94, v94, v6
	v_lshlrev_b64 v[96:97], 2, v[4:5]
	v_lshl_add_u64 v[2:3], s[12:13], 0, v[94:95]
	v_or_b32_e32 v96, v96, v6
	v_lshl_add_u64 v[2:3], v[2:3], 0, s[4:5]
	v_lshl_add_u64 v[4:5], s[12:13], 0, v[96:97]
	v_lshl_add_u64 v[4:5], v[4:5], 0, s[4:5]
	global_load_dwordx4 v[12:15], v[2:3], off nt
	global_load_dwordx4 v[8:11], v[4:5], off nt
	v_add_u32_e32 v2, 0x3800, v0
	v_ashrrev_i32_e32 v3, 31, v2
	v_add_u32_e32 v0, 0x3c00, v0
	v_lshlrev_b64 v[98:99], 2, v[2:3]
	v_ashrrev_i32_e32 v1, 31, v0
	v_or_b32_e32 v98, v98, v6
	v_lshlrev_b64 v[102:103], 2, v[0:1]
	v_lshl_add_u64 v[2:3], s[12:13], 0, v[98:99]
	v_or_b32_e32 v102, v102, v6
	v_lshl_add_u64 v[100:101], v[2:3], 0, s[4:5]
	v_lshl_add_u64 v[0:1], s[12:13], 0, v[102:103]
	v_add_u32_e32 v152, s91, v6
	v_lshl_add_u64 v[104:105], v[0:1], 0, s[4:5]
	global_load_dwordx4 v[4:7], v[100:101], off nt
	global_load_dwordx4 v[0:3], v[104:105], off nt
	s_and_saveexec_b64 s[10:11], s[2:3]
	s_cbranch_execz .LBB0_326
	v_lshl_add_u64 v[176:177], v[68:69], 1, s[8:9]
	v_readlane_b32 s24, v254, 15
	v_readlane_b32 s25, v254, 16
	s_load_dwordx2 s[24:25], s[24:25], 0x58
	v_add_co_u32_e32 v186, vcc, 0xc180000, v176
	s_nop 1
	v_addc_co_u32_e32 v187, vcc, 0, v177, vcc
	global_load_ushort v183, v[186:187], off
	v_add_u32_e32 v186, s15, v68
	v_ashrrev_i32_e32 v187, 31, v186
	s_waitcnt lgkmcnt(0)
	v_lshl_add_u64 v[186:187], v[186:187], 2, s[24:25]
	global_load_dword v184, v[186:187], off
	v_add_co_u32_e32 v178, vcc, 0x4080000, v176
	s_nop 1
	v_addc_co_u32_e32 v179, vcc, 0, v177, vcc
	global_load_ushort v180, v[178:179], off
	v_add_co_u32_e32 v178, vcc, 0x8100000, v176
	s_nop 1
	v_addc_co_u32_e32 v179, vcc, 0, v177, vcc
	global_load_ushort v181, v[178:179], off
	global_load_ushort v182, v[176:177], off
	s_waitcnt vmcnt(2)
	v_lshlrev_b32_e32 v176, 16, v180
	v_mul_f32_e32 v176, 0x3fb8aa3b, v176
	v_exp_f32_e32 v176, v176
	s_waitcnt vmcnt(0)
	v_lshlrev_b32_e32 v177, 16, v182
	ds_write2st64_b32 v83, v177, v176 offset1:2
	v_sub_f32_e32 v176, 1.0, v176
	v_lshlrev_b32_e32 v177, 16, v181
	ds_write2st64_b32 v83, v176, v177 offset0:4 offset1:6

.LBB0_330:
	s_or_b64 exec, exec, s[10:11]
	s_waitcnt lgkmcnt(0)
	s_barrier
	s_and_saveexec_b64 s[10:11], s[2:3]
	s_cbranch_execz .LBB0_323
	v_readlane_b32 s2, v254, 15
	v_lshlrev_b64 v[2:3], 1, v[68:69]
	v_readlane_b32 s3, v254, 16
	v_lshl_add_u64 v[4:5], s[8:9], 0, v[2:3]
	s_load_dwordx2 s[2:3], s[2:3], 0x58
	v_add_co_u32_e32 v4, vcc, 0xc180000, v4
	s_nop 1
	v_addc_co_u32_e32 v5, vcc, 0, v5, vcc
	v_add_u32_e32 v4, s15, v68
	v_ashrrev_i32_e32 v5, 31, v4
	s_waitcnt lgkmcnt(0)
	v_lshl_add_u64 v[4:5], v[4:5], 2, s[2:3]
	v_mov_b32_e32 v4, s91
	ds_read_b64 v[4:5], v4 offset:6144
	s_lshl_b64 s[2:3], s[6:7], 12
	s_add_u32 s2, s18, s2
	s_addc_u32 s3, s19, s3
	s_waitcnt lgkmcnt(0)
	v_add_f32_e32 v4, v4, v5
	v_fmamk_f32 v4, v4, 0x3c000000, v80
	v_mul_f32_e32 v5, 0x4b800000, v4
	v_cmp_gt_f32_e32 vcc, s21, v4
	v_lshlrev_b32_e32 v1, 16, v183
	v_cndmask_b32_e32 v4, v4, v5, vcc
	v_rsq_f32_e32 v4, v4
	s_nop 0
	v_mul_f32_e32 v5, 0x45800000, v4
	v_cndmask_b32_e32 v4, v4, v5, vcc
	v_mul_f32_e32 v0, v0, v4
	v_mul_f32_e32 v0, v184, v0
	v_mul_f32_e32 v0, v0, v1
	v_cvt_pk_bf16_f32 v4, v0, s0
	v_lshl_add_u64 v[0:1], s[2:3], 0, v[2:3]
	global_store_short v[0:1], v4, off
	s_branch .LBB0_323
